# v121 + FFN-up and W_in tile headers: 32-bit scalar tile index and next-tile test instead of 64-bit arithmetic with VALU compares (15 fewer instructions per tile)
# speedup vs baseline: 1.0005x; 1.0005x over previous
;     __device__ bool next(int i, Unit& u) const { Unit t; if (!base.next(i >> 2, t)) return false; const int br = i & 3; u.pm = br * 64 + t.pm; u.pn = br * 4 + t.pn; return true; }
;     __host__ __device__ bool next(int i, Unit& u) const {
;         const long L = (long)i * G + c; if (L >= nwg) return false;
;         int wgid = (int)L; { const int q = nwg / NXCD, r = nwg % NXCD, xcd = wgid % NXCD, off = wgid / NXCD; wgid = (xcd < r ? xcd * (q + 1) : r * (q + 1) + (xcd - r) * q) + off; }
;         const int nig = WGM * nN, gid = wgid / nig, fm = gid * WGM, gsz = (nM - fm) < WGM ? (nM - fm) : WGM;
;         u.pm = fm + ((wgid % nig) % gsz); u.pn = (wgid % nig) / gsz; return true;
.LBB0_1127:
	s_add_i32 s1, s1, 1
	s_mul_i32 s80, s1, s60
	s_add_i32 s80, s80, s58
	s_cmp_lt_u32 s80, 0x600
	s_cselect_b64 s[2:3], -1, 0
	s_cbranch_scc0 .LBB0_1129
	s_lshr_b32 s9, s80, 3
	s_and_b32 s5, s80, 7
	s_mulk_i32 s5, 0xc0
	s_add_i32 s5, s5, s9
	s_mul_hi_u32 s9, s5, 0x2aaaaaab
	s_lshr_b32 s9, s9, 5
	s_lshl_b32 s22, s9, 3
	s_mulk_i32 s9, 0xc0
	s_sub_i32 s5, s5, s9
	s_lshr_b32 s76, s5, 3
	s_and_b32 s5, s5, 7
	s_add_i32 s78, s22, s5
	v_readlane_b32 s77, v255, 2
	s_and_b32 s77, s77, 7
	s_lshl_b32 s77, s77, 2
	s_add_i32 s76, s76, s77
	s_cmp_ge_u32 s76, 24
	s_cselect_b32 s77, 24, 0
	s_sub_i32 s76, s76, s77
	s_cmp_ge_u32 s76, 24
	s_cselect_b32 s77, 24, 0
	s_sub_i32 s76, s76, s77

;     __device__ bool next(int i, Unit& u) const { Unit t; if (!base.next(i >> 2, t)) return false; const int br = i & 3; u.pm = br * 64 + t.pm; u.pn = br * 4 + t.pn; return true; }
;     __host__ __device__ bool next(int i, Unit& u) const {
;         const long L = (long)i * G + c; if (L >= nwg) return false;
;         int wgid = (int)L; { const int q = nwg / NXCD, r = nwg % NXCD, xcd = wgid % NXCD, off = wgid / NXCD; wgid = (xcd < r ? xcd * (q + 1) : r * (q + 1) + (xcd - r) * q) + off; }
;         const int nig = WGM * nN, gid = wgid / nig, fm = gid * WGM, gsz = (nM - fm) < WGM ? (nM - fm) : WGM;
;         u.pm = fm + ((wgid % nig) % gsz); u.pn = (wgid % nig) / gsz; return true;
.LBB0_1353:
	s_add_i32 s59, s59, 1
	s_mul_i32 s12, s59, s60
	s_add_i32 s12, s12, s58
	s_cmp_lt_u32 s12, 0xb00
	s_cselect_b64 s[2:3], -1, 0
	s_cbranch_scc0 .LBB0_1355
	s_lshr_b32 s9, s12, 3
	s_and_b32 s8, s12, 7
	s_mulk_i32 s8, 0x160
	s_add_i32 s8, s8, s9
	s_mul_hi_u32 s9, s8, 0x2e8ba2e9
	s_lshr_b32 s9, s9, 5
	s_lshl_b32 s10, s9, 3
	s_mulk_i32 s9, 0xb0
	s_sub_i32 s9, s8, s9
	s_lshr_b32 s8, s9, 3
	s_and_b32 s9, s9, 7
	s_add_i32 s10, s10, s9
